# phase-3 loop PV: the 8 V^T-fragment ds_reads per half also issued up front into private quads with counted lgkmcnt
# speedup vs baseline: 1.0088x; 1.0004x over previous
; #define MFMA16(a, b, c) __builtin_amdgcn_mfma_f32_16x16x32_f16((a), (b), (c), 0, 0, 0)
; DI void qk_tile2(f32x4 (&sa)[4], f32x4 (&sb)[4], const char* sK, const bf16x8 (&qa)[2], const bf16x8 (&qb)[2], int lr, int g) {
; #pragma unroll
;   for (int kt = 0; kt < 4; ++kt) {
;     const bf16x8 k0 = *(const bf16x8*)(sK + (kt * 16 + lr) * 128 + ((g ^ ((lr >> 1) & 7)) << 4)), k1 = *(const bf16x8*)(sK + (kt * 16 + lr) * 128 + (((4 + g) ^ ((lr >> 1) & 7)) << 4));
;     sa[kt] = MFMA16(k0, qa[0], ((f32x4){0.f, 0.f, 0.f, 0.f})); sb[kt] = MFMA16(k0, qb[0], ((f32x4){0.f, 0.f, 0.f, 0.f}));
;     sa[kt] = MFMA16(k1, qa[1], sa[kt]); sb[kt] = MFMA16(k1, qb[1], sb[kt]);
;   }
; }
; DI float softmax_step(f32x4 (&st)[4], float& m, float& lsum) {
;   float mx = fmaxf(fmaxf(fmaxf(st[0][0], st[0][1]), fmaxf(st[0][2], st[0][3])), fmaxf(fmaxf(st[1][0], st[1][1]), fmaxf(st[1][2], st[1][3])));
;   mx = fmaxf(mx, fmaxf(fmaxf(fmaxf(st[2][0], st[2][1]), fmaxf(st[2][2], st[2][3])), fmaxf(fmaxf(st[3][0], st[3][1]), fmaxf(st[3][2], st[3][3]))));
;   mx = fmaxf(mx, __shfl_xor(mx, 16)); mx = fmaxf(mx, __shfl_xor(mx, 32));
.LBB0_1079:
	v_readlane_b32 s16, v254, 55
	s_add_i32 s1, s15, -2
	v_readlane_b32 s18, v254, 57
	v_readlane_b32 s19, v254, 58
	v_cmp_le_i32_e32 vcc, s1, v107
	v_readlane_b32 s17, v254, 56
	v_lshl_add_u64 v[122:123], s[18:19], 0, v[112:113]
	s_and_saveexec_b64 s[12:13], vcc
	s_cbranch_execz .LBB0_1081
	v_add_co_u32_e32 v80, vcc, 0x1b900000, v122
	s_mov_b32 s16, 0xff800000
	s_nop 0
	v_addc_co_u32_e32 v81, vcc, 0, v123, vcc
	global_load_dwordx2 v[126:127], v[80:81], off
	v_add_co_u32_e32 v80, vcc, 0x1b902000, v122
	s_waitcnt vmcnt(0)
	v_lshrrev_b32_e32 v147, v132, v126
	v_addc_co_u32_e32 v81, vcc, 0, v123, vcc
	global_load_dwordx2 v[128:129], v[80:81], off
	ds_read_b128 v[200:203], v139
	ds_read_b128 v[204:207], v140
	ds_read_b128 v[208:211], v139 offset:2048
	ds_read_b128 v[212:215], v140 offset:2048
	ds_read_b128 v[220:223], v139 offset:4096
	ds_read_b128 v[224:227], v140 offset:4096
	ds_read_b128 v[228:231], v139 offset:6144
	ds_read_b128 v[232:235], v140 offset:6144
	s_waitcnt lgkmcnt(7)
	v_mfma_f32_16x16x32_f16 v[88:91], v[200:203], v[0:3], 0
	v_and_b32_e32 v130, 1, v147
	v_cmp_eq_u32_e32 vcc, 1, v130
	v_bfe_i32 v141, v147, 1, 1
	v_mfma_f32_16x16x32_f16 v[80:83], v[200:203], v[4:7], 0
	v_lshrrev_b32_e32 v126, v138, v126
	s_waitcnt lgkmcnt(6)
	v_mfma_f32_16x16x32_f16 v[142:145], v[204:207], v[8:11], v[88:91]
	v_mfma_f32_16x16x32_f16 v[154:157], v[204:207], v[12:15], v[80:83]
	s_nop 3
	s_waitcnt lgkmcnt(5)
	v_mfma_f32_16x16x32_f16 v[88:91], v[208:211], v[0:3], 0
	v_mfma_f32_16x16x32_f16 v[80:83], v[208:211], v[4:7], 0
	s_waitcnt lgkmcnt(4)
	v_mfma_f32_16x16x32_f16 v[100:103], v[212:215], v[8:11], v[88:91]
	v_mfma_f32_16x16x32_f16 v[96:99], v[212:215], v[12:15], v[80:83]
	s_nop 4
	s_waitcnt lgkmcnt(3)
	v_mfma_f32_16x16x32_f16 v[84:87], v[220:223], v[0:3], 0
	v_mfma_f32_16x16x32_f16 v[80:83], v[220:223], v[4:7], 0
	s_waitcnt lgkmcnt(2)
	v_mfma_f32_16x16x32_f16 v[84:87], v[224:227], v[8:11], v[84:87]
	v_mfma_f32_16x16x32_f16 v[80:83], v[224:227], v[12:15], v[80:83]
	s_waitcnt lgkmcnt(1)
	v_mfma_f32_16x16x32_f16 v[158:161], v[228:231], v[0:3], 0
	v_mfma_f32_16x16x32_f16 v[162:165], v[228:231], v[4:7], 0
	s_waitcnt lgkmcnt(0)
	v_mfma_f32_16x16x32_f16 v[88:91], v[232:235], v[8:11], v[158:161]
	s_nop 4
	v_cndmask_b32_e32 v159, v187, v142, vcc
	v_bfe_i32 v142, v147, 2, 1
	v_mfma_f32_16x16x32_f16 v[92:95], v[232:235], v[12:15], v[162:165]
	s_waitcnt vmcnt(0)
	v_lshrrev_b32_e32 v158, v132, v128
	v_and_b32_e32 v130, 1, v158
	v_cmp_eq_u32_e32 vcc, 1, v130
	v_lshrrev_b32_e32 v128, v138, v128
	s_nop 0
	v_cndmask_b32_e32 v130, v187, v154, vcc
	v_bfi_b32 v154, v141, v143, v187
	v_and_b32_e32 v141, 2, v158
	v_cmp_ne_u32_e32 vcc, 0, v141
	v_bfe_i32 v143, v147, 3, 1
	v_bfe_i32 v147, v126, 0, 1
	v_cndmask_b32_e32 v141, v187, v155, vcc
	v_bfi_b32 v144, v142, v144, v187
	v_and_b32_e32 v142, 4, v158
	v_cmp_ne_u32_e32 vcc, 0, v142
	s_nop 1
	v_cndmask_b32_e32 v142, v187, v156, vcc
	v_bfi_b32 v145, v143, v145, v187
	v_and_b32_e32 v143, 8, v158
	v_cmp_ne_u32_e32 vcc, 0, v143
	s_nop 1
	v_cndmask_b32_e32 v143, v187, v157, vcc
	v_bfi_b32 v100, v147, v100, v187
	v_and_b32_e32 v147, 1, v128
	v_cmp_eq_u32_e32 vcc, 1, v147
	s_nop 1
	v_cndmask_b32_e32 v147, v187, v96, vcc
	v_and_b32_e32 v96, 2, v126
	v_cmp_ne_u32_e32 vcc, 0, v96
	s_nop 1
	v_cndmask_b32_e32 v96, v187, v101, vcc
	v_bfe_i32 v101, v128, 1, 1
	v_bfi_b32 v97, v101, v97, v187
	v_and_b32_e32 v101, 4, v126
	v_cmp_ne_u32_e32 vcc, 0, v101
	s_nop 1
	v_cndmask_b32_e32 v101, v187, v102, vcc
	v_bfe_i32 v102, v128, 2, 1
	v_bfi_b32 v98, v102, v98, v187
	v_and_b32_e32 v102, 8, v126
	v_lshrrev_b32_e32 v126, v132, v129
	v_cmp_ne_u32_e32 vcc, 0, v102
	s_nop 1
	v_cndmask_b32_e32 v102, v187, v103, vcc
	v_and_b32_e32 v103, 8, v128
	v_cmp_ne_u32_e32 vcc, 0, v103
	s_nop 1
	v_cndmask_b32_e32 v103, v187, v99, vcc
	v_lshrrev_b32_e32 v99, v132, v127
	v_bfe_i32 v128, v99, 0, 1
	v_bfi_b32 v84, v128, v84, v187
	v_and_b32_e32 v128, 1, v126
	v_cmp_eq_u32_e32 vcc, 1, v128
	s_nop 1
	v_cndmask_b32_e32 v128, v187, v80, vcc
	v_and_b32_e32 v80, 2, v99
	v_cmp_ne_u32_e32 vcc, 0, v80
	s_nop 1
	v_cndmask_b32_e32 v80, v187, v85, vcc
	v_bfe_i32 v85, v126, 1, 1
	v_bfi_b32 v81, v85, v81, v187
	v_and_b32_e32 v85, 4, v99
	v_cmp_ne_u32_e32 vcc, 0, v85
	s_nop 1
	v_cndmask_b32_e32 v85, v187, v86, vcc
	v_bfe_i32 v86, v126, 2, 1
	v_bfi_b32 v155, v86, v82, v187
	v_bfe_i32 v86, v126, 3, 1
	v_and_b32_e32 v82, 8, v99
	v_cmp_ne_u32_e32 vcc, 0, v82
	s_nop 1
	v_cndmask_b32_e32 v82, v187, v87, vcc
	v_bfi_b32 v83, v86, v83, v187
	v_lshrrev_b32_e32 v86, v138, v127
	v_lshrrev_b32_e32 v87, v138, v129
	v_bfe_i32 v99, v86, 0, 1
	v_bfi_b32 v88, v99, v88, v187
	v_bfe_i32 v99, v87, 0, 1
	v_bfi_b32 v126, v99, v92, v187
	v_bfe_i32 v92, v86, 1, 1
	v_bfi_b32 v89, v92, v89, v187
	v_bfe_i32 v92, v87, 1, 1
	v_bfi_b32 v127, v92, v93, v187
	v_bfe_i32 v92, v86, 2, 1
	v_bfe_i32 v86, v86, 3, 1
	v_bfi_b32 v93, v92, v90, v187
	v_bfe_i32 v90, v87, 2, 1
	v_bfi_b32 v129, v90, v94, v187
	v_bfi_b32 v91, v86, v91, v187
	v_bfe_i32 v86, v87, 3, 1
	v_bfi_b32 v156, v86, v95, v187
	v_max_f32_e32 v86, v144, v145
	v_max_f32_e32 v87, v101, v102
	v_max_f32_e32 v90, v84, v80
	v_max_f32_e32 v92, v85, v82
	v_max_f32_e32 v94, v93, v91
	v_max3_f32 v94, v88, v89, v94
	v_max3_f32 v86, v159, v154, v86
	v_max3_f32 v87, v100, v96, v87
	v_max3_f32 v90, v90, v92, v94
	v_max3_f32 v86, v86, v87, v90
	v_mov_b32_e32 v87, v86
	s_waitcnt lgkmcnt(0)
	s_nop 1
	v_permlane16_swap_b32_e32 v86, v87
	v_max_f32_e32 v86, v86, v87
	v_mov_b32_e32 v87, v86
	s_waitcnt lgkmcnt(0)
; DI float softmax_step(f32x4 (&st)[4], float& m, float& lsum) {
;   float mx = fmaxf(fmaxf(fmaxf(st[0][0], st[0][1]), fmaxf(st[0][2], st[0][3])), fmaxf(fmaxf(st[1][0], st[1][1]), fmaxf(st[1][2], st[1][3])));
;   mx = fmaxf(mx, fmaxf(fmaxf(fmaxf(st[2][0], st[2][1]), fmaxf(st[2][2], st[2][3])), fmaxf(fmaxf(st[3][0], st[3][1]), fmaxf(st[3][2], st[3][3]))));
;   mx = fmaxf(mx, __shfl_xor(mx, 16)); mx = fmaxf(mx, __shfl_xor(mx, 32));
;   const float mn = fmaxf(m, mx);
;   const float mu = mn == -INFINITY ? 0.f : mn;
;   const float alpha = __builtin_amdgcn_exp2f(m - mu);
;   float ps = 0.f;
; #pragma unroll
;   for (int kt = 0; kt < 4; ++kt)
; #pragma unroll
;     for (int j = 0; j < 4; ++j) { const float p = __builtin_amdgcn_exp2f(st[kt][j] - mu); st[kt][j] = p; ps += p; }
;   lsum = lsum * alpha + ps; m = mn;
;   return alpha;
; }
	s_nop 1
	v_permlane32_swap_b32_e32 v86, v87
	v_max3_f32 v99, v131, v86, v87
	v_cmp_neq_f32_e32 vcc, s16, v99
	s_nop 1
	v_cndmask_b32_e32 v87, 0, v99, vcc
	v_sub_f32_e32 v86, v159, v87
	v_exp_f32_e32 v162, v86
	v_sub_f32_e32 v86, v154, v87
	v_exp_f32_e32 v164, v86
	v_sub_f32_e32 v86, v144, v87
	v_exp_f32_e32 v166, v86
	v_sub_f32_e32 v86, v145, v87
	v_sub_f32_e32 v80, v80, v87
	v_exp_f32_e32 v168, v86
	v_sub_f32_e32 v86, v100, v87
	v_exp_f32_e32 v94, v80
	v_sub_f32_e32 v80, v85, v87
	v_exp_f32_e32 v170, v86
	v_sub_f32_e32 v86, v96, v87
	v_exp_f32_e32 v92, v80
	v_sub_f32_e32 v80, v82, v87
	v_exp_f32_e32 v190, v86
	v_sub_f32_e32 v86, v101, v87
	v_exp_f32_e32 v90, v80
	v_sub_f32_e32 v80, v88, v87
	v_exp_f32_e32 v192, v86
	v_sub_f32_e32 v86, v102, v87
	v_exp_f32_e32 v88, v80
	v_sub_f32_e32 v80, v89, v87
	v_exp_f32_e32 v194, v86
	v_sub_f32_e32 v84, v84, v87
	v_exp_f32_e32 v86, v80
	v_sub_f32_e32 v80, v93, v87
	v_exp_f32_e32 v96, v84
	v_exp_f32_e32 v82, v80
	v_sub_f32_e32 v80, v91, v87
	v_sub_f32_e32 v84, v131, v87
	v_max_f32_e32 v85, v142, v143
	v_max_f32_e32 v87, v98, v103
	v_max_f32_e32 v89, v128, v81
	v_max_f32_e32 v91, v155, v83
	v_max_f32_e32 v93, v129, v156
	v_max3_f32 v93, v126, v127, v93
	v_max3_f32 v85, v130, v141, v85
	v_max3_f32 v87, v147, v97, v87
	v_max3_f32 v89, v89, v91, v93
	v_max3_f32 v85, v85, v87, v89
	v_mov_b32_e32 v87, v85
	v_exp_f32_e32 v84, v84
	v_exp_f32_e32 v80, v80
	v_mov_b32_e32 v131, v99
	s_waitcnt lgkmcnt(0)
	s_nop 1
	v_permlane16_swap_b32_e32 v85, v87
	v_max_f32_e32 v85, v85, v87
	v_mov_b32_e32 v87, v85
	s_waitcnt lgkmcnt(0)
	s_nop 1
	v_permlane32_swap_b32_e32 v85, v87
	v_max3_f32 v102, v146, v85, v87
	v_cmp_neq_f32_e32 vcc, s16, v102
	s_nop 1
	v_cndmask_b32_e32 v85, 0, v102, vcc
	v_sub_f32_e32 v87, v130, v85
	v_exp_f32_e32 v163, v87
	v_sub_f32_e32 v87, v141, v85
	v_exp_f32_e32 v165, v87
	v_sub_f32_e32 v87, v142, v85
	v_exp_f32_e32 v167, v87
	v_sub_f32_e32 v87, v143, v85
	v_exp_f32_e32 v169, v87
	v_sub_f32_e32 v87, v147, v85
	v_sub_f32_e32 v81, v81, v85
	v_exp_f32_e32 v171, v87
	v_sub_f32_e32 v87, v97, v85
	v_exp_f32_e32 v95, v81
	v_sub_f32_e32 v81, v155, v85
	v_exp_f32_e32 v191, v87
	v_sub_f32_e32 v87, v98, v85
	v_exp_f32_e32 v93, v81
	v_sub_f32_e32 v81, v83, v85
	v_exp_f32_e32 v193, v87
	v_sub_f32_e32 v87, v103, v85
	v_exp_f32_e32 v91, v81
	v_sub_f32_e32 v81, v126, v85
	v_exp_f32_e32 v195, v87
	v_sub_f32_e32 v87, v128, v85
	v_exp_f32_e32 v89, v81
	v_sub_f32_e32 v81, v127, v85
	v_exp_f32_e32 v97, v87
	v_exp_f32_e32 v87, v81
	v_sub_f32_e32 v81, v129, v85
	v_exp_f32_e32 v83, v81
	v_sub_f32_e32 v81, v156, v85
	v_sub_f32_e32 v85, v146, v85
	v_exp_f32_e32 v98, v85
	v_pk_mul_f32 v[156:157], v[70:71], v[84:85] op_sel_hi:[1,0]
	v_pk_mul_f32 v[154:155], v[68:69], v[84:85] op_sel_hi:[1,0]
	v_pk_mul_f32 v[128:129], v[62:63], v[84:85] op_sel_hi:[1,0]
	v_pk_mul_f32 v[142:143], v[56:57], v[98:99] op_sel_hi:[1,0]
	v_pk_mul_f32 v[70:71], v[50:51], v[98:99] op_sel_hi:[1,0]
	v_pk_mul_f32 v[68:69], v[48:49], v[98:99] op_sel_hi:[1,0]
	v_pk_mul_f32 v[50:51], v[74:75], v[84:85] op_sel_hi:[1,0]
	v_pk_mul_f32 v[48:49], v[72:73], v[84:85] op_sel_hi:[1,0]
	v_pk_add_f32 v[56:57], v[162:163], 0 op_sel_hi:[1,0]
	ds_read_b128 v[200:203], v139 offset:9216
	ds_read_b128 v[204:207], v139 offset:11264
	ds_read_b128 v[208:211], v139 offset:13312
	ds_read_b128 v[212:215], v139 offset:15360
	ds_read_b128 v[220:223], v140 offset:9216
	ds_read_b128 v[224:227], v140 offset:11264
	ds_read_b128 v[228:231], v140 offset:15360
	ds_read_b128 v[232:235], v140 offset:13312
	v_pk_add_f32 v[56:57], v[164:165], v[56:57]
	v_pk_mul_f32 v[126:127], v[60:61], v[84:85] op_sel_hi:[1,0]
	v_pk_add_f32 v[56:57], v[166:167], v[56:57]
	v_pk_mul_f32 v[144:145], v[58:59], v[98:99] op_sel_hi:[1,0]
	v_pk_add_f32 v[56:57], v[168:169], v[56:57]
	v_cvt_pk_f16_f32 v58, v170, v190
	v_pk_add_f32 v[56:57], v[170:171], v[56:57]
	v_cvt_pk_f16_f32 v59, v192, v194
	v_pk_add_f32 v[56:57], v[190:191], v[56:57]
	v_pk_mul_f32 v[160:161], v[66:67], v[98:99] op_sel_hi:[1,0]
	v_pk_add_f32 v[56:57], v[192:193], v[56:57]
	v_pk_mul_f32 v[158:159], v[64:65], v[98:99] op_sel_hi:[1,0]
	v_pk_add_f32 v[56:57], v[194:195], v[56:57]
	v_pk_mul_f32 v[66:67], v[54:55], v[84:85] op_sel_hi:[1,0]
	v_pk_add_f32 v[100:101], v[96:97], v[56:57]
	v_cvt_pk_f16_f32 v56, v162, v164
	v_cvt_pk_f16_f32 v57, v166, v168
	v_pk_mul_f32 v[64:65], v[52:53], v[84:85] op_sel_hi:[1,0]
	v_pk_mul_f32 v[54:55], v[78:79], v[98:99] op_sel_hi:[1,0]
	v_pk_mul_f32 v[52:53], v[76:77], v[98:99] op_sel_hi:[1,0]
	s_waitcnt lgkmcnt(7)
	v_mfma_f32_16x16x32_f16 v[76:79], v[200:203], v[56:59], v[126:129]
	v_cvt_pk_f16_f32 v60, v163, v165
	v_cvt_pk_f16_f32 v61, v167, v169
	v_cvt_pk_f16_f32 v62, v171, v191
	v_cvt_pk_f16_f32 v63, v193, v195
	v_exp_f32_e32 v81, v81
	v_cvt_pk_f16_f32 v190, v96, v94
	v_mfma_f32_16x16x32_f16 v[72:75], v[200:203], v[60:63], v[142:145]
	v_cvt_pk_f16_f32 v191, v92, v90
	v_cvt_pk_f16_f32 v192, v88, v86
	v_cvt_pk_f16_f32 v193, v82, v80
	s_waitcnt lgkmcnt(6)
	v_mfma_f32_16x16x32_f16 v[142:145], v[204:207], v[56:59], v[154:157]
	v_cvt_pk_f16_f32 v194, v97, v95
	v_cvt_pk_f16_f32 v195, v93, v91
	s_nop 0
	v_mfma_f32_16x16x32_f16 v[126:129], v[204:207], v[60:63], v[158:161]
	v_cvt_pk_f16_f32 v196, v89, v87
	v_cvt_pk_f16_f32 v197, v83, v81
	v_pk_add_f32 v[94:95], v[94:95], v[100:101]
	s_waitcnt lgkmcnt(5)
	v_mfma_f32_16x16x32_f16 v[158:161], v[208:211], v[56:59], v[64:67]
	s_nop 2
	v_pk_add_f32 v[92:93], v[92:93], v[94:95]
	v_mov_b32_e32 v85, v98
	s_waitcnt lgkmcnt(4)
	v_mfma_f32_16x16x32_f16 v[162:165], v[212:215], v[56:59], v[48:51]
	s_nop 2
	v_pk_add_f32 v[90:91], v[90:91], v[92:93]
	v_mov_b32_e32 v146, v102
	v_mfma_f32_16x16x32_f16 v[154:157], v[208:211], v[60:63], v[68:71]
	v_add_f32_e64 v88, v88, v90
	v_add_f32_e64 v89, v89, v91
	v_pk_add_f32 v[86:87], v[86:87], v[88:89]
	v_mfma_f32_16x16x32_f16 v[166:169], v[212:215], v[60:63], v[52:55]
	v_add_f32_e64 v82, v82, v86
	v_add_f32_e64 v83, v83, v87
	v_pk_add_f32 v[80:81], v[80:81], v[82:83]
	s_waitcnt lgkmcnt(3)
	v_mfma_f32_16x16x32_f16 v[60:63], v[220:223], v[190:193], v[76:79]
	v_fma_f32 v118, v118, v84, v80
	v_fma_f32 v119, v119, v85, v81
	v_mfma_f32_16x16x32_f16 v[56:59], v[220:223], v[194:197], v[72:75]
	s_waitcnt lgkmcnt(2)
	v_mfma_f32_16x16x32_f16 v[68:71], v[224:227], v[190:193], v[142:145]
	v_mfma_f32_16x16x32_f16 v[64:67], v[224:227], v[194:197], v[126:129]
	s_waitcnt lgkmcnt(0)
	v_mfma_f32_16x16x32_f16 v[52:55], v[232:235], v[190:193], v[158:161]
	v_mfma_f32_16x16x32_f16 v[48:51], v[232:235], v[194:197], v[154:157]
	v_mfma_f32_16x16x32_f16 v[72:75], v[228:231], v[190:193], v[162:165]
	v_mfma_f32_16x16x32_f16 v[76:79], v[228:231], v[194:197], v[166:169]

; #define MFMA16(a, b, c) __builtin_amdgcn_mfma_f32_16x16x32_f16((a), (b), (c), 0, 0, 0)
; DI void qk_tile2(f32x4 (&sa)[4], f32x4 (&sb)[4], const char* sK, const bf16x8 (&qa)[2], const bf16x8 (&qb)[2], int lr, int g) {
; #pragma unroll
;   for (int kt = 0; kt < 4; ++kt) {
;     const bf16x8 k0 = *(const bf16x8*)(sK + (kt * 16 + lr) * 128 + ((g ^ ((lr >> 1) & 7)) << 4)), k1 = *(const bf16x8*)(sK + (kt * 16 + lr) * 128 + (((4 + g) ^ ((lr >> 1) & 7)) << 4));
;     sa[kt] = MFMA16(k0, qa[0], ((f32x4){0.f, 0.f, 0.f, 0.f})); sb[kt] = MFMA16(k0, qb[0], ((f32x4){0.f, 0.f, 0.f, 0.f}));
;     sa[kt] = MFMA16(k1, qa[1], sa[kt]); sb[kt] = MFMA16(k1, qb[1], sb[kt]);
;   }
; }
; DI float softmax_step(f32x4 (&st)[4], float& m, float& lsum) {
;   float mx = fmaxf(fmaxf(fmaxf(st[0][0], st[0][1]), fmaxf(st[0][2], st[0][3])), fmaxf(fmaxf(st[1][0], st[1][1]), fmaxf(st[1][2], st[1][3])));
;   mx = fmaxf(mx, fmaxf(fmaxf(fmaxf(st[2][0], st[2][1]), fmaxf(st[2][2], st[2][3])), fmaxf(fmaxf(st[3][0], st[3][1]), fmaxf(st[3][2], st[3][3]))));
;   mx = fmaxf(mx, __shfl_xor(mx, 16)); mx = fmaxf(mx, __shfl_xor(mx, 32));
.LBB0_1085:
	v_add_co_u32_e32 v80, vcc, 0x1b900000, v122
	s_mov_b32 s1, 0xff800000
	s_nop 0
	v_addc_co_u32_e32 v81, vcc, 0, v123, vcc
	global_load_dwordx2 v[128:129], v[80:81], off offset:8
	v_add_co_u32_e32 v80, vcc, 0x1b902000, v122
	s_nop 1
	v_addc_co_u32_e32 v81, vcc, 0, v123, vcc
	global_load_dwordx2 v[144:145], v[80:81], off offset:8
	ds_read_b128 v[200:203], v139 offset:18432
	ds_read_b128 v[204:207], v140 offset:18432
	ds_read_b128 v[208:211], v139 offset:20480
	ds_read_b128 v[212:215], v140 offset:20480
	ds_read_b128 v[220:223], v139 offset:22528
	ds_read_b128 v[224:227], v140 offset:22528
	ds_read_b128 v[228:231], v139 offset:24576
	ds_read_b128 v[232:235], v140 offset:24576
	s_waitcnt lgkmcnt(7)
	v_mfma_f32_16x16x32_f16 v[88:91], v[200:203], v[0:3], 0
	v_mfma_f32_16x16x32_f16 v[80:83], v[200:203], v[4:7], 0
	s_waitcnt lgkmcnt(6)
	v_mfma_f32_16x16x32_f16 v[88:91], v[204:207], v[8:11], v[88:91]
	v_mfma_f32_16x16x32_f16 v[80:83], v[204:207], v[12:15], v[80:83]
	s_waitcnt lgkmcnt(5)
	v_mfma_f32_16x16x32_f16 v[96:99], v[208:211], v[0:3], 0
	v_mfma_f32_16x16x32_f16 v[84:87], v[208:211], v[4:7], 0
	s_waitcnt lgkmcnt(4)
	v_mfma_f32_16x16x32_f16 v[96:99], v[212:215], v[8:11], v[96:99]
	v_mfma_f32_16x16x32_f16 v[84:87], v[212:215], v[12:15], v[84:87]
	s_waitcnt lgkmcnt(3)
	v_mfma_f32_16x16x32_f16 v[120:123], v[220:223], v[0:3], 0
	v_mfma_f32_16x16x32_f16 v[92:95], v[220:223], v[4:7], 0
	s_waitcnt lgkmcnt(2)
	v_mfma_f32_16x16x32_f16 v[120:123], v[224:227], v[8:11], v[120:123]
	v_mfma_f32_16x16x32_f16 v[92:95], v[224:227], v[12:15], v[92:95]
	s_waitcnt lgkmcnt(1)
	v_mfma_f32_16x16x32_f16 v[154:157], v[228:231], v[0:3], 0
	v_mfma_f32_16x16x32_f16 v[100:103], v[228:231], v[4:7], 0
	s_waitcnt lgkmcnt(0)
	v_mfma_f32_16x16x32_f16 v[154:157], v[232:235], v[8:11], v[154:157]
	v_mfma_f32_16x16x32_f16 v[100:103], v[232:235], v[12:15], v[100:103]
	s_waitcnt vmcnt(1)
	v_lshrrev_b32_e32 v124, v132, v128
	v_bfe_i32 v126, v124, 0, 1
	v_bfi_b32 v88, v126, v88, v187
	s_waitcnt vmcnt(0)
	v_lshrrev_b32_e32 v125, v132, v144
	v_bfe_i32 v126, v125, 0, 1
	v_bfi_b32 v80, v126, v80, v187
	v_bfe_i32 v126, v124, 1, 1
	v_bfi_b32 v89, v126, v89, v187
	v_bfe_i32 v126, v125, 1, 1
	v_bfi_b32 v81, v126, v81, v187
	v_bfe_i32 v126, v124, 2, 1
	v_bfe_i32 v124, v124, 3, 1
	v_bfi_b32 v90, v126, v90, v187
	v_bfe_i32 v126, v125, 2, 1
	v_bfi_b32 v82, v126, v82, v187
	v_bfi_b32 v91, v124, v91, v187
	v_bfe_i32 v124, v125, 3, 1
	v_lshrrev_b32_e32 v125, v138, v144
	v_bfi_b32 v83, v124, v83, v187
	v_lshrrev_b32_e32 v124, v138, v128
	v_bfe_i32 v126, v124, 0, 1
	v_bfi_b32 v96, v126, v96, v187
	v_bfe_i32 v126, v125, 0, 1
	v_bfi_b32 v127, v126, v84, v187
	v_bfe_i32 v84, v124, 1, 1
	v_bfi_b32 v97, v84, v97, v187
	v_bfe_i32 v84, v125, 1, 1
	v_bfi_b32 v147, v84, v85, v187
	v_bfe_i32 v84, v124, 2, 1
	v_bfi_b32 v85, v84, v98, v187
	v_bfe_i32 v84, v125, 2, 1
	v_bfi_b32 v98, v84, v86, v187
	v_bfe_i32 v84, v124, 3, 1
	v_bfi_b32 v99, v84, v99, v187
	v_bfe_i32 v84, v125, 3, 1
	v_lshrrev_b32_e32 v86, v132, v145
	v_bfi_b32 v125, v84, v87, v187
	v_lshrrev_b32_e32 v84, v132, v129
	v_and_b32_e32 v87, 1, v84
	v_cmp_eq_u32_e32 vcc, 1, v87
	s_nop 1
	v_cndmask_b32_e32 v87, v187, v120, vcc
	v_bfe_i32 v120, v86, 0, 1
	v_bfi_b32 v92, v120, v92, v187
	v_and_b32_e32 v120, 2, v84
	v_cmp_ne_u32_e32 vcc, 0, v120
	s_nop 1
	v_cndmask_b32_e32 v120, v187, v121, vcc
	v_bfe_i32 v121, v86, 1, 1
	v_bfi_b32 v93, v121, v93, v187
	v_and_b32_e32 v121, 4, v84
	v_bfe_i32 v84, v84, 3, 1
	v_cmp_ne_u32_e32 vcc, 0, v121
	s_nop 1
	v_cndmask_b32_e32 v121, v187, v122, vcc
	v_bfe_i32 v122, v86, 2, 1
	v_bfi_b32 v94, v122, v94, v187
	v_bfi_b32 v122, v84, v123, v187
	v_bfe_i32 v84, v86, 3, 1
	v_lshrrev_b32_e32 v86, v138, v145
	v_bfi_b32 v95, v84, v95, v187
	v_lshrrev_b32_e32 v84, v138, v129
	v_and_b32_e32 v123, 1, v84
	v_cmp_eq_u32_e32 vcc, 1, v123
	v_bfe_i32 v124, v86, 0, 1
	s_nop 0
	v_cndmask_b32_e32 v123, v187, v154, vcc
	v_bfi_b32 v129, v124, v100, v187
	v_bfe_i32 v124, v86, 1, 1
	v_and_b32_e32 v100, 2, v84
	v_cmp_ne_u32_e32 vcc, 0, v100
	s_nop 1
	v_cndmask_b32_e32 v100, v187, v155, vcc
	v_bfi_b32 v101, v124, v101, v187
	v_bfe_i32 v124, v84, 2, 1
	v_bfe_i32 v84, v84, 3, 1
	v_bfi_b32 v128, v124, v156, v187
	v_bfe_i32 v124, v86, 2, 1
	v_bfi_b32 v102, v124, v102, v187
	v_bfi_b32 v130, v84, v157, v187
	v_bfe_i32 v84, v86, 3, 1
	v_bfi_b32 v103, v84, v103, v187
	v_max_f32_e32 v84, v90, v91
	v_max_f32_e32 v86, v85, v99
	v_max_f32_e32 v124, v87, v120
	v_max_f32_e32 v126, v121, v122
	v_max_f32_e32 v144, v128, v130
	v_max3_f32 v144, v123, v100, v144
	v_max3_f32 v84, v88, v89, v84
	v_max3_f32 v86, v96, v97, v86
	v_max3_f32 v124, v124, v126, v144
	v_max3_f32 v84, v84, v86, v124
	v_mov_b32_e32 v86, v84
	s_waitcnt lgkmcnt(0)
	s_nop 1
	v_permlane16_swap_b32_e32 v84, v86
	v_max_f32_e32 v84, v84, v86
	v_mov_b32_e32 v86, v84
	s_waitcnt lgkmcnt(0)
	s_nop 1
	v_permlane32_swap_b32_e32 v84, v86
	v_max3_f32 v144, v131, v84, v86
	v_cmp_neq_f32_e32 vcc, s1, v144
	s_nop 1
	v_cndmask_b32_e32 v145, 0, v144, vcc
	v_sub_f32_e32 v84, v88, v145
	v_sub_f32_e32 v88, v90, v145
	v_exp_f32_e32 v162, v88
	v_sub_f32_e32 v88, v91, v145
	v_sub_f32_e32 v85, v85, v145
	v_exp_f32_e32 v164, v88
	v_sub_f32_e32 v88, v96, v145
	v_exp_f32_e32 v170, v85
	v_sub_f32_e32 v85, v99, v145
	v_exp_f32_e32 v166, v88
	v_sub_f32_e32 v88, v97, v145
	v_exp_f32_e32 v190, v85
	v_sub_f32_e32 v85, v87, v145
	v_exp_f32_e32 v168, v88
	v_exp_f32_e32 v88, v85
	v_sub_f32_e32 v85, v120, v145
	v_exp_f32_e32 v90, v85
	v_sub_f32_e32 v85, v121, v145
	v_exp_f32_e32 v120, v85
	v_sub_f32_e32 v85, v122, v145
	v_exp_f32_e32 v122, v85
	v_sub_f32_e32 v85, v123, v145
	v_exp_f32_e32 v124, v85
	v_sub_f32_e32 v85, v100, v145
	v_exp_f32_e32 v126, v85
	v_sub_f32_e32 v85, v128, v145
	v_exp_f32_e32 v128, v85
	v_sub_f32_e32 v85, v130, v145
	v_exp_f32_e32 v130, v85
	v_sub_f32_e32 v85, v131, v145
	v_exp_f32_e32 v100, v85
	v_sub_f32_e32 v86, v89, v145
	v_max_f32_e32 v85, v82, v83
	v_max_f32_e32 v87, v98, v125
	v_max_f32_e32 v89, v92, v93
	v_max_f32_e32 v91, v94, v95
	v_max_f32_e32 v96, v102, v103
	v_max3_f32 v96, v129, v101, v96
	v_max3_f32 v85, v80, v81, v85
	v_max3_f32 v87, v127, v147, v87
	v_max3_f32 v89, v89, v91, v96
	v_max3_f32 v85, v85, v87, v89
	v_mov_b32_e32 v87, v85
	v_exp_f32_e32 v84, v84
	v_exp_f32_e32 v86, v86
	v_pk_mul_f32 v[70:71], v[70:71], v[100:101] op_sel_hi:[1,0]
	v_pk_mul_f32 v[68:69], v[68:69], v[100:101] op_sel_hi:[1,0]
	s_waitcnt lgkmcnt(0)
; DI float softmax_step(f32x4 (&st)[4], float& m, float& lsum) {
;   float mx = fmaxf(fmaxf(fmaxf(st[0][0], st[0][1]), fmaxf(st[0][2], st[0][3])), fmaxf(fmaxf(st[1][0], st[1][1]), fmaxf(st[1][2], st[1][3])));
;   mx = fmaxf(mx, fmaxf(fmaxf(fmaxf(st[2][0], st[2][1]), fmaxf(st[2][2], st[2][3])), fmaxf(fmaxf(st[3][0], st[3][1]), fmaxf(st[3][2], st[3][3]))));
;   mx = fmaxf(mx, __shfl_xor(mx, 16)); mx = fmaxf(mx, __shfl_xor(mx, 32));
;   const float mn = fmaxf(m, mx);
;   const float mu = mn == -INFINITY ? 0.f : mn;
;   const float alpha = __builtin_amdgcn_exp2f(m - mu);
;   float ps = 0.f;
; #pragma unroll
;   for (int kt = 0; kt < 4; ++kt)
; #pragma unroll
;     for (int j = 0; j < 4; ++j) { const float p = __builtin_amdgcn_exp2f(st[kt][j] - mu); st[kt][j] = p; ps += p; }
;   lsum = lsum * alpha + ps; m = mn;
;   return alpha;
; }
	s_nop 1
	v_permlane16_swap_b32_e32 v85, v87
	v_max_f32_e32 v85, v85, v87
	v_mov_b32_e32 v87, v85
	v_pk_mul_f32 v[156:157], v[54:55], v[100:101] op_sel_hi:[1,0]
	v_pk_mul_f32 v[154:155], v[52:53], v[100:101] op_sel_hi:[1,0]
	s_waitcnt lgkmcnt(0)
	s_nop 1
	v_permlane32_swap_b32_e32 v85, v87
	v_max3_f32 v145, v146, v85, v87
	v_cmp_neq_f32_e32 vcc, s1, v145
	s_nop 1
	v_cndmask_b32_e32 v96, 0, v145, vcc
	v_sub_f32_e32 v80, v80, v96
	v_exp_f32_e32 v85, v80
	v_sub_f32_e32 v80, v81, v96
	v_exp_f32_e32 v87, v80
	v_sub_f32_e32 v80, v82, v96
	v_exp_f32_e32 v163, v80
	v_sub_f32_e32 v80, v83, v96
	v_exp_f32_e32 v165, v80
	v_sub_f32_e32 v80, v127, v96
	v_exp_f32_e32 v167, v80
	v_sub_f32_e32 v80, v147, v96
	v_exp_f32_e32 v169, v80
	v_sub_f32_e32 v80, v98, v96
	v_exp_f32_e32 v171, v80
	v_sub_f32_e32 v80, v125, v96
	v_exp_f32_e32 v191, v80
	v_sub_f32_e32 v80, v92, v96
	v_exp_f32_e32 v89, v80
	v_sub_f32_e32 v80, v93, v96
	v_exp_f32_e32 v91, v80
	v_sub_f32_e32 v80, v94, v96
	v_exp_f32_e32 v121, v80
	v_sub_f32_e32 v80, v95, v96
	v_exp_f32_e32 v123, v80
	v_sub_f32_e32 v80, v129, v96
	v_exp_f32_e32 v125, v80
	v_sub_f32_e32 v80, v101, v96
	v_exp_f32_e32 v127, v80
	v_sub_f32_e32 v80, v102, v96
	v_exp_f32_e32 v129, v80
	v_sub_f32_e32 v80, v103, v96
	v_exp_f32_e32 v131, v80
	v_sub_f32_e32 v80, v146, v96
	v_exp_f32_e32 v102, v80
	v_pk_mul_f32 v[82:83], v[62:63], v[100:101] op_sel_hi:[1,0]
	v_pk_mul_f32 v[80:81], v[60:61], v[100:101] op_sel_hi:[1,0]
	v_cvt_pk_f16_f32 v60, v84, v86
	v_pk_mul_f32 v[160:161], v[50:51], v[102:103] op_sel_hi:[1,0]
	v_pk_mul_f32 v[158:159], v[48:49], v[102:103] op_sel_hi:[1,0]
	v_pk_mul_f32 v[50:51], v[74:75], v[100:101] op_sel_hi:[1,0]
	v_pk_mul_f32 v[48:49], v[72:73], v[100:101] op_sel_hi:[1,0]
	ds_read_b128 v[200:203], v139 offset:29696
	ds_read_b128 v[204:207], v139 offset:27648
	ds_read_b128 v[208:211], v139 offset:33792
	ds_read_b128 v[212:215], v139 offset:31744
	ds_read_b128 v[220:223], v140 offset:27648
	ds_read_b128 v[224:227], v140 offset:29696
	ds_read_b128 v[228:231], v140 offset:31744
	ds_read_b128 v[232:235], v140 offset:33792
	v_pk_mul_f32 v[92:93], v[56:57], v[102:103] op_sel_hi:[1,0]
	v_pk_add_f32 v[56:57], v[84:85], 0 op_sel_hi:[1,0]
	v_pk_mul_f32 v[98:99], v[66:67], v[102:103] op_sel_hi:[1,0]
	v_pk_add_f32 v[56:57], v[86:87], v[56:57]
	v_pk_mul_f32 v[96:97], v[64:65], v[102:103] op_sel_hi:[1,0]
	v_pk_add_f32 v[56:57], v[162:163], v[56:57]
	v_cvt_pk_f16_f32 v61, v162, v164
	v_pk_add_f32 v[56:57], v[164:165], v[56:57]
	v_cvt_pk_f16_f32 v62, v166, v168
	v_pk_add_f32 v[56:57], v[166:167], v[56:57]
	v_cvt_pk_f16_f32 v63, v170, v190
	v_pk_add_f32 v[56:57], v[168:169], v[56:57]
	v_cvt_pk_f16_f32 v84, v85, v87
	v_pk_add_f32 v[56:57], v[170:171], v[56:57]
	v_cvt_pk_f16_f32 v85, v163, v165
	v_cvt_pk_f16_f32 v86, v167, v169
	v_cvt_pk_f16_f32 v87, v171, v191
	v_pk_add_f32 v[56:57], v[190:191], v[56:57]
	s_waitcnt lgkmcnt(7)
	v_mfma_f32_16x16x32_f16 v[68:71], v[200:203], v[60:63], v[68:71]
	v_add_f32_e64 v56, v88, v56
	v_add_f32_e64 v57, v89, v57
	v_pk_mul_f32 v[94:95], v[58:59], v[102:103] op_sel_hi:[1,0]
	v_pk_add_f32 v[56:57], v[90:91], v[56:57]
	v_mfma_f32_16x16x32_f16 v[72:75], v[200:203], v[84:87], v[96:99]
	v_add_f32_e64 v56, v120, v56
	v_add_f32_e64 v57, v121, v57
	v_pk_mul_f32 v[54:55], v[78:79], v[102:103] op_sel_hi:[1,0]
	v_pk_add_f32 v[56:57], v[122:123], v[56:57]
	s_nop 0
	v_pk_add_f32 v[56:57], v[124:125], v[56:57]
	v_pk_mul_f32 v[52:53], v[76:77], v[102:103] op_sel_hi:[1,0]
	v_pk_add_f32 v[56:57], v[126:127], v[56:57]
	v_mov_b32_e32 v101, v102
	v_pk_add_f32 v[56:57], v[128:129], v[56:57]
	v_mov_b32_e32 v146, v145
	v_pk_add_f32 v[102:103], v[130:131], v[56:57]
	s_waitcnt lgkmcnt(6)
	v_mfma_f32_16x16x32_f16 v[56:59], v[204:207], v[60:63], v[80:83]
	v_fma_f32 v118, v118, v100, v102
	v_fma_f32 v119, v119, v101, v103
	s_nop 0
	v_mfma_f32_16x16x32_f16 v[64:67], v[204:207], v[84:87], v[92:95]
	s_waitcnt lgkmcnt(5)
	v_mfma_f32_16x16x32_f16 v[92:95], v[208:211], v[60:63], v[48:51]
	s_nop 2
	s_waitcnt lgkmcnt(4)
	v_mfma_f32_16x16x32_f16 v[76:79], v[212:215], v[60:63], v[154:157]
	v_mfma_f32_16x16x32_f16 v[80:83], v[212:215], v[84:87], v[158:161]
	v_mfma_f32_16x16x32_f16 v[84:87], v[208:211], v[84:87], v[52:55]
	v_cvt_pk_f16_f32 v96, v88, v90
	v_cvt_pk_f16_f32 v97, v120, v122
	v_cvt_pk_f16_f32 v98, v124, v126
	v_cvt_pk_f16_f32 v99, v128, v130
	v_cvt_pk_f16_f32 v88, v89, v91
	v_cvt_pk_f16_f32 v89, v121, v123
	v_cvt_pk_f16_f32 v90, v125, v127
	v_cvt_pk_f16_f32 v91, v129, v131
	s_waitcnt lgkmcnt(3)
	v_mfma_f32_16x16x32_f16 v[60:63], v[220:223], v[96:99], v[56:59]
	v_mov_b32_e32 v131, v144
	v_mfma_f32_16x16x32_f16 v[56:59], v[220:223], v[88:91], v[64:67]
	s_waitcnt lgkmcnt(2)
	v_mfma_f32_16x16x32_f16 v[68:71], v[224:227], v[96:99], v[68:71]
	v_mfma_f32_16x16x32_f16 v[64:67], v[224:227], v[88:91], v[72:75]
	s_waitcnt lgkmcnt(1)
	v_mfma_f32_16x16x32_f16 v[52:55], v[228:231], v[96:99], v[76:79]
	s_nop 2
	v_mfma_f32_16x16x32_f16 v[48:51], v[228:231], v[88:91], v[80:83]
	s_waitcnt lgkmcnt(0)
	v_mfma_f32_16x16x32_f16 v[72:75], v[232:235], v[96:99], v[92:95]
	v_mfma_f32_16x16x32_f16 v[76:79], v[232:235], v[88:91], v[84:87]
	s_or_b64 exec, exec, s[12:13]
	s_andn2_b64 vcc, exec, s[10:11]
	s_cbranch_vccnz .LBB0_1076
